# seams PA->PB, PB->PC, PC->PD, PE->PF: L1 invalidate dropped (no line of the consumer's input can be resident: the producer phase never loads it and the previous kept invalidate precedes it); PD->PE, P
# baseline (speedup 1.0000x reference)
; __device__ __forceinline__ unsigned xb_ld(unsigned* p)              { return __hip_atomic_load(p, __ATOMIC_RELAXED, __HIP_MEMORY_SCOPE_AGENT); }
; __device__ __forceinline__ unsigned xb_add(unsigned* p, unsigned v) { return __hip_atomic_fetch_add(p, v, __ATOMIC_RELAXED, __HIP_MEMORY_SCOPE_AGENT); }
; #define XB_SPIN(cond, bar) do { unsigned _sp = 0; while (cond) { __builtin_amdgcn_s_sleep(1); \
;     if ((++_sp & 255u) == 0u) { if (xb_ld(&(bar)[XB_TMO])) break; if (_sp > XB_SPIN_CAP) { atomicAdd(&(bar)[XB_TMO], 1u); break; } } } } while (0)
; __device__ __forceinline__ void xcd_barrier(const XcdBarrier& b) {
;     asm volatile("s_waitcnt vmcnt(0)" ::: "memory");
;     __syncthreads();
;     if (threadIdx.x == 0) {
;         unsigned* bar = b.bar;
;         __builtin_amdgcn_s_waitcnt(0);
;         unsigned nloc = b.st[0], nx = b.st[1];
;         if (nloc == 0u) { xcd_barrier_complete(bar, b.x, nloc, nx); b.st[0] = nloc; b.st[1] = nx; }
;         const unsigned old = xb_add(&bar[XB_XSUB(b.x)], 1u);
;         const unsigned gen = old / nloc;
;         if (old + 1u == (gen + 1u) * nloc) {
;             __builtin_amdgcn_fence(__ATOMIC_RELEASE, "agent");
;             asm volatile("s_waitcnt vmcnt(0)" ::: "memory");
;             const unsigned og = xb_add(&bar[XB_TOP], 1u);
;             const unsigned tg = og / nx;
;             if (og + 1u == (tg + 1u) * nx) xb_add(&bar[XB_TOPGEN], 1u);
;             else XB_SPIN(xb_ld(&bar[XB_TOPGEN]) == tg, bar);
;             __builtin_amdgcn_fence(__ATOMIC_ACQUIRE, "agent");
;             xb_add(&bar[XB_XGEN(b.x)], 1u);
;             asm volatile("s_waitcnt vmcnt(0)" ::: "memory");
;         } else {
;             XB_SPIN(xb_ld(&bar[XB_XGEN(b.x)]) == gen, bar);
;             __builtin_amdgcn_fence(__ATOMIC_ACQUIRE, "agent");
;             asm volatile("s_waitcnt vmcnt(0)" ::: "memory");
;         }
;     }
;     __syncthreads();
; }
.LBB0_225:
	s_xor_b64 s[6:7], s[50:51], -1
	v_writelane_b32 v238, s6, 51
	s_nop 1
	v_writelane_b32 v238, s7, 52
	s_nop 0
	v_readlane_b32 s6, v238, 44
	s_add_i32 s23, s6, 2
	s_cmp_lt_i32 s23, s5
	s_cselect_b64 s[36:37], -1, 0
	s_and_b64 s[24:25], s[40:41], s[36:37]
	s_andn2_b64 vcc, exec, s[24:25]
	s_cbranch_vccnz .LBB0_279
	s_waitcnt vmcnt(0)
	v_readlane_b32 s6, v242, 38
	v_readlane_b32 s7, v242, 39
	s_waitcnt vmcnt(0) lgkmcnt(0)
	s_barrier
	s_and_saveexec_b64 s[38:39], s[6:7]
	s_cbranch_execz .LBB0_278
	v_readlane_b32 s6, v242, 52
	v_readlane_b32 s7, v242, 53
	s_nop 3
	s_cmp_eq_u64 s[6:7], 0
	s_cbranch_scc0 .Lpa_seam_grid
	v_readlane_b32 s6, v240, 60
	v_readlane_b32 s7, v240, 61
	v_mov_b32_e32 v3, 1
	s_nop 4
	global_atomic_add v66, v3, s[6:7] offset:512
	s_cmp_ge_u32 s101, 5
	s_cselect_b32 s100, 2, 1
	v_readlane_b32 s6, v239, 63
	v_readlane_b32 s7, v241, 0
	v_readlane_b32 s98, v242, 4
	s_nop 3
	s_and_b32 s99, s98, 7
	s_lshl_b32 s99, s99, 3
	s_bfe_u32 s98, s98, 0x30003
	s_add_i32 s98, s98, s99
	s_mov_b32 s99, 0

; __device__ __forceinline__ unsigned xb_ld(unsigned* p)              { return __hip_atomic_load(p, __ATOMIC_RELAXED, __HIP_MEMORY_SCOPE_AGENT); }
; __device__ __forceinline__ unsigned xb_add(unsigned* p, unsigned v) { return __hip_atomic_fetch_add(p, v, __ATOMIC_RELAXED, __HIP_MEMORY_SCOPE_AGENT); }
; #define XB_SPIN(cond, bar) do { unsigned _sp = 0; while (cond) { __builtin_amdgcn_s_sleep(1); \
;     if ((++_sp & 255u) == 0u) { if (xb_ld(&(bar)[XB_TMO])) break; if (_sp > XB_SPIN_CAP) { atomicAdd(&(bar)[XB_TMO], 1u); break; } } } } while (0)
; __device__ __forceinline__ void xcc_local_barrier(unsigned* bar2, unsigned x, unsigned nloc, unsigned* tmobar) {
;     asm volatile("s_waitcnt vmcnt(0)" ::: "memory");
;     __syncthreads();
;     if (threadIdx.x == 0) {
;         const unsigned old = xb_add(&bar2[XB_XSUB(x)], 1u);
;         const unsigned gen = old / nloc;
;         if (old + 1u == (gen + 1u) * nloc) (void)xb_add(&bar2[XB_XGEN(x)], 1u);
;         else XB_SPIN(xb_ld(&bar2[XB_XGEN(x)]) == gen, tmobar);
;         __builtin_amdgcn_fence(__ATOMIC_ACQUIRE, "agent");
;         asm volatile("s_waitcnt vmcnt(0)" ::: "memory");
;     }
;     __syncthreads();
; }
.LBB0_478:
	s_and_b64 vcc, exec, s[38:39]
	s_cbranch_vccz .LBB0_498
	v_readlane_b32 s6, v238, 25
	s_nop 1
	v_mov_b32_e32 v2, s6
	ds_read_b32 v2, v2
	s_waitcnt vmcnt(0)
	v_readlane_b32 s6, v242, 38
	v_readlane_b32 s7, v242, 39
	s_waitcnt vmcnt(0) lgkmcnt(0)
	s_barrier
	s_and_saveexec_b64 s[38:39], s[6:7]
	s_cbranch_execz .LBB0_497
	s_cmp_ge_u32 s101, 5
	s_cselect_b32 s88, 2, 1
	s_lshl_b32 s88, s88, 8
	s_add_i32 s101, s101, 1
	v_readlane_b32 s6, v239, 63
	v_readlane_b32 s7, v241, 0
	v_readlane_b32 s98, v242, 4
	v_mov_b32_e32 v3, s101
	s_nop 3
	s_lshr_b32 s98, s98, 6
	s_lshl_b32 s98, s98, 2
	v_mov_b32_e32 v4, s98
	global_store_dword v4, v3, s[6:7] offset:128 sc1
	v_readlane_b32 s12, v240, 60
	v_readlane_b32 s13, v240, 61
	s_mov_b32 s100, 0
	s_nop 4

; __device__ __forceinline__ unsigned xb_ld(unsigned* p)              { return __hip_atomic_load(p, __ATOMIC_RELAXED, __HIP_MEMORY_SCOPE_AGENT); }
; __device__ __forceinline__ unsigned xb_add(unsigned* p, unsigned v) { return __hip_atomic_fetch_add(p, v, __ATOMIC_RELAXED, __HIP_MEMORY_SCOPE_AGENT); }
; #define XB_SPIN(cond, bar) do { unsigned _sp = 0; while (cond) { __builtin_amdgcn_s_sleep(1); \
;     if ((++_sp & 255u) == 0u) { if (xb_ld(&(bar)[XB_TMO])) break; if (_sp > XB_SPIN_CAP) { atomicAdd(&(bar)[XB_TMO], 1u); break; } } } } while (0)
; __device__ __forceinline__ void xcc_local_barrier(unsigned* bar2, unsigned x, unsigned nloc, unsigned* tmobar) {
;     asm volatile("s_waitcnt vmcnt(0)" ::: "memory");
;     __syncthreads();
;     if (threadIdx.x == 0) {
;         const unsigned old = xb_add(&bar2[XB_XSUB(x)], 1u);
;         const unsigned gen = old / nloc;
;         if (old + 1u == (gen + 1u) * nloc) (void)xb_add(&bar2[XB_XGEN(x)], 1u);
;         else XB_SPIN(xb_ld(&bar2[XB_XGEN(x)]) == gen, tmobar);
;         __builtin_amdgcn_fence(__ATOMIC_ACQUIRE, "agent");
;         asm volatile("s_waitcnt vmcnt(0)" ::: "memory");
;     }
;     __syncthreads();
; }
.LBB0_612:
	s_and_b64 vcc, exec, s[40:41]
	s_cbranch_vccz .LBB0_632
	v_readlane_b32 s6, v238, 25
	s_nop 1
	v_mov_b32_e32 v2, s6
	ds_read_b32 v2, v2
	s_waitcnt vmcnt(0)
	v_readlane_b32 s6, v242, 38
	v_readlane_b32 s7, v242, 39
	s_waitcnt vmcnt(0) lgkmcnt(0)
	s_barrier
	s_and_saveexec_b64 s[40:41], s[6:7]
	s_cbranch_execz .LBB0_631
	s_add_i32 s101, s101, 1
	v_readlane_b32 s6, v239, 63
	v_readlane_b32 s7, v241, 0
	v_readlane_b32 s98, v242, 4
	v_mov_b32_e32 v3, s101
	s_nop 3
	s_lshr_b32 s98, s98, 6
	s_lshl_b32 s98, s98, 2
	v_mov_b32_e32 v4, s98
	global_store_dword v4, v3, s[6:7] offset:128 sc1
	s_mov_b32 s100, 0

; __device__ __forceinline__ unsigned xb_ld(unsigned* p)              { return __hip_atomic_load(p, __ATOMIC_RELAXED, __HIP_MEMORY_SCOPE_AGENT); }
; __device__ __forceinline__ unsigned xb_add(unsigned* p, unsigned v) { return __hip_atomic_fetch_add(p, v, __ATOMIC_RELAXED, __HIP_MEMORY_SCOPE_AGENT); }
; #define XB_SPIN(cond, bar) do { unsigned _sp = 0; while (cond) { __builtin_amdgcn_s_sleep(1); \
;     if ((++_sp & 255u) == 0u) { if (xb_ld(&(bar)[XB_TMO])) break; if (_sp > XB_SPIN_CAP) { atomicAdd(&(bar)[XB_TMO], 1u); break; } } } } while (0)
; __device__ __forceinline__ void xcc_local_barrier(unsigned* bar2, unsigned x, unsigned nloc, unsigned* tmobar) {
;     asm volatile("s_waitcnt vmcnt(0)" ::: "memory");
;     __syncthreads();
;     if (threadIdx.x == 0) {
;         const unsigned old = xb_add(&bar2[XB_XSUB(x)], 1u);
;         const unsigned gen = old / nloc;
;         if (old + 1u == (gen + 1u) * nloc) (void)xb_add(&bar2[XB_XGEN(x)], 1u);
;         else XB_SPIN(xb_ld(&bar2[XB_XGEN(x)]) == gen, tmobar);
;         __builtin_amdgcn_fence(__ATOMIC_ACQUIRE, "agent");
;         asm volatile("s_waitcnt vmcnt(0)" ::: "memory");
;     }
;     __syncthreads();
; }
.LBB0_874:
	s_and_b64 vcc, exec, s[38:39]
	s_cbranch_vccz .LBB0_894
	v_readlane_b32 s6, v238, 25
	s_nop 1
	v_mov_b32_e32 v2, s6
	ds_read_b32 v2, v2
	s_waitcnt vmcnt(0)
	v_readlane_b32 s6, v242, 38
	v_readlane_b32 s7, v242, 39
	s_waitcnt vmcnt(0) lgkmcnt(0)
	s_barrier
	s_and_saveexec_b64 s[38:39], s[6:7]
	s_cbranch_execz .LBB0_893
	v_readlane_b32 s6, v240, 60
	v_readlane_b32 s7, v240, 61
	v_mov_b32_e32 v3, 1
	s_nop 4
	global_atomic_add v66, v3, s[6:7] offset:576
	s_add_i32 s101, s101, 1
	v_readlane_b32 s6, v239, 63
	v_readlane_b32 s7, v241, 0
	v_readlane_b32 s98, v242, 4
	v_mov_b32_e32 v3, s101
	s_nop 3
	s_lshr_b32 s98, s98, 6
	s_lshl_b32 s98, s98, 2
	v_mov_b32_e32 v4, s98
	global_store_dword v4, v3, s[6:7] offset:128 sc1
	s_mov_b32 s100, 0
